# grid barrier: XCD leaders add to the cross-XCD counter without return and every workgroup polls that counter (no separate generation word, hand-written tail)
# baseline (speedup 1.0000x reference)
.LBB0_735:
	s_or_b64 exec, exec, s[4:5]
	v_cvt_f32_u32_e32 v5, v3
	s_waitcnt vmcnt(0)
	v_readfirstlane_b32 s2, v4
	v_sub_u32_e32 v4, 0, v3
	v_rcp_iflag_f32_e32 v5, v5
	v_add_u32_e32 v6, s2, v0
	v_mul_f32_e32 v5, 0x4f7ffffe, v5
	v_cvt_u32_f32_e32 v5, v5
	v_mul_lo_u32 v0, v4, v5
	v_mul_hi_u32 v0, v5, v0
	v_add_u32_e32 v0, v5, v0
	v_mul_hi_u32 v0, v6, v0
	v_mul_lo_u32 v4, v0, v3
	v_sub_u32_e32 v4, v6, v4
	v_add_u32_e32 v5, 1, v0
	v_cmp_ge_u32_e32 vcc, v4, v3
	s_nop 1
	v_cndmask_b32_e32 v0, v0, v5, vcc
	v_sub_u32_e32 v5, v4, v3
	v_cndmask_b32_e32 v4, v4, v5, vcc
	v_add_u32_e32 v5, 1, v0
	v_cmp_ge_u32_e32 vcc, v4, v3
	v_add_u32_e32 v4, 1, v6
	s_nop 0
	v_cndmask_b32_e32 v0, v0, v5, vcc
	v_mul_lo_u32 v5, v3, v0
	v_add_u32_e32 v3, v5, v3
	v_cmp_ne_u32_e32 vcc, v4, v3
	s_waitcnt lgkmcnt(0)
	v_add_u32_e32 v5, 1, v0
	v_readlane_b32 s6, v237, 45
	v_readlane_b32 s7, v237, 46
	v_mul_lo_u32 v5, v5, v2
	s_cbranch_vccnz .Lgb_poll
	buffer_wbl2 sc1
	v_mov_b32_e32 v6, 1
	s_waitcnt vmcnt(0)
	global_atomic_add v1, v6, s[6:7]
.Lgb_poll:
	s_mov_b32 s2, 0
	s_nop 2
.Lgb_spin:
	global_load_dword v6, v1, s[6:7] sc1
	s_add_i32 s2, s2, 1
	s_waitcnt vmcnt(0)
	v_sub_u32_e32 v6, v6, v5
	v_cmp_gt_i32_e32 vcc, 0, v6
	s_cbranch_vccz .Lgb_done
	s_cmp_lt_u32 s2, 0x40000
	s_cbranch_scc0 .Lgb_done
	s_sleep 1
	s_branch .Lgb_spin
.Lgb_done:
	buffer_inv sc1
	s_waitcnt vmcnt(0)
	s_branch .LBB0_20
